# P7: leading half runs the epilogue front (tap loads, m=3 scaling, halo write) before its compensating barrier, overlapping the trailing half's last MFMA block
# baseline (speedup 1.0000x reference)
;     __device__ __forceinline__ void operator()(const f32x4 (&acc)[2][2][4][2], const Unit& u, int wr, int wc, int fr, int fq) const {
;         constexpr int FF = 2816, FF2 = 5632;
;         const int lcol = wc * 32 + 8 * fq, gcol = u.pn * HALF + lcol;
;         float rs[2][4];
;         load_rs(slots, u.pm * BM + wr * 64, fr, fq, 1.0f, rs);
;         if (fr >= 14) {
; #pragma unroll
;             for (int ai = 0; ai < 2; ++ai)
; #pragma unroll
;                 for (int bj = 0; bj < 2; ++bj)
; #pragma unroll
;                     for (int n = 0; n < 2; ++n) { const f32x4 x = acc[ai][bj][3][n] * rs[ai][3];
;                         *(PG8_LAS f32x4*)(halo + ((ai * 2 + wr) * 2 + (fr - 14)) * 256 + bj * HALF + lcol + 4 * n) = x;
;                         if (ai == 1 && wr == 1) *(f32x4*)(rawh + (size_t)(u.pm * 2 + (fr - 14)) * FF2 + bj * FF + gcol + 4 * n) = x; }
;         }
;         f32x4 w0[2], w1[2], w2[2], bb[2];
; #pragma unroll
;         for (int bj = 0; bj < 2; ++bj) { const int col = bj * FF + gcol;
;             w0[bj] = *(const f32x4*)(cw + col); w1[bj] = *(const f32x4*)(cw + FF2 + col); w2[bj] = *(const f32x4*)(cw + 2 * FF2 + col); bb[bj] = *(const f32x4*)(cb + col); }
;         asm volatile("s_waitcnt lgkmcnt(0)" ::: "memory"); __builtin_amdgcn_s_barrier(); asm volatile("" ::: "memory");
;         unsigned pk_lo[2][4][2];
; #pragma unroll
;         for (int n = 0; n < 2; ++n) {
;             if (n == 1) {
; #pragma unroll
;                 for (int bj = 0; bj < 2; ++bj) { const int col = bj * FF + gcol + 4;
;                     w0[bj] = *(const f32x4*)(cw + col); w1[bj] = *(const f32x4*)(cw + FF2 + col); w2[bj] = *(const f32x4*)(cw + 2 * FF2 + col); bb[bj] = *(const f32x4*)(cb + col); } }
; #pragma unroll
;             for (int ai = 0; ai < 2; ++ai) {
;                 f32x4 pg[2]; const int pb = ai * 2 + wr - 1;
; #pragma unroll
;                 for (int bj = 0; bj < 2; ++bj) { pg[bj] = (f32x4){0.f, 0.f, 0.f, 0.f};
;                     if (pb >= 0 && fr >= 14) pg[bj] = *(const PG8_LAS f32x4*)(halo + (pb * 2 + (fr - 14)) * 256 + bj * HALF + lcol + 4 * n); }
; template <class Epi, class Sched, bool ALIGN_EPI = false, bool SP2 = false>
; __device__ __forceinline__ void gemm_phase(PG8_LAS unsigned char* lds, const Gemm g, const Sched& S, const Epi& E, int wave_in) {
;     ...
;         if constexpr (ALIGN_EPI) { if (wr == 0) PG8_BAR; }
.Lkexit_6:
.LBB0_900:
	v_readlane_b32 s18, v255, 37
	v_readlane_b32 s19, v255, 38
	s_lshl_b32 s5, s71, 8
	s_add_i32 s5, s5, s8
	s_lshl_b32 s11, s71, 1
	s_movk_i32 s29, 0x1600
	s_mov_b32 s100, 0xbfb8aa3b
	s_mov_b32 s79, 0
	v_cmp_eq_u32_e64 s[98:99], 15, v206
	v_lshl_or_b32 v233, s69, 7, v208
	v_lshlrev_b32_e32 v237, 2, v206
	v_lshlrev_b32_e32 v233, 2, v233
	v_or_b32_e32 v239, s5, v206
	v_add_u32_e32 v235, 0x2c00, v233
	global_load_dwordx4 v[128:131], v233, s[14:15]
	global_load_dwordx4 v[132:135], v233, s[16:17]
	global_load_dwordx4 v[136:139], v233, s[92:93]
	global_load_dwordx4 v[140:143], v233, s[60:61]
	global_load_dwordx4 v[144:147], v235, s[14:15]
	global_load_dwordx4 v[148:151], v235, s[16:17]
	global_load_dwordx4 v[152:155], v235, s[92:93]
	global_load_dwordx4 v[156:159], v235, s[60:61]
	v_lshrrev_b32_e32 v243, 1, v233
	v_add_u32_e32 v241, s11, v206
	v_mad_u32_u24 v239, v239, s29, v243
	v_mad_u32_u24 v241, v241, s70, v233
	s_cmp_eq_u32 s101, s71
	v_add_u32_e32 v249, 0x2c00, v241
	s_cbranch_scc1 .Lp7_rsok
	v_or_b32_e32 v229, s5, v209
	v_lshlrev_b32_e32 v229, 6, v229
	v_add_u32_e32 v231, 0x2000, v229
	global_load_dwordx4 v[160:163], v229, s[26:27]
	global_load_dwordx4 v[164:167], v229, s[26:27] offset:16
	global_load_dwordx4 v[178:181], v229, s[26:27] offset:32
	global_load_dwordx4 v[182:185], v229, s[26:27] offset:48
	global_load_dwordx4 v[186:189], v231, s[26:27]
	global_load_dwordx4 v[194:197], v231, s[26:27] offset:16
	global_load_dwordx4 v[198:201], v231, s[26:27] offset:32
	global_load_dwordx4 v[202:205], v231, s[26:27] offset:48
	s_waitcnt vmcnt(0)
	v_pk_add_f32 v[162:163], v[162:163], v[166:167]
	v_pk_add_f32 v[188:189], v[188:189], v[196:197]
	v_pk_add_f32 v[160:161], v[160:161], v[164:165]
	v_pk_add_f32 v[186:187], v[186:187], v[194:195]
	v_pk_add_f32 v[164:165], v[180:181], v[184:185]
	v_pk_add_f32 v[194:195], v[200:201], v[204:205]
	v_pk_add_f32 v[166:167], v[178:179], v[182:183]
	v_pk_add_f32 v[196:197], v[198:199], v[202:203]
	v_pk_add_f32 v[162:163], v[162:163], v[164:165]
	v_pk_add_f32 v[188:189], v[188:189], v[194:195]
	v_pk_add_f32 v[160:161], v[160:161], v[166:167]
	v_pk_add_f32 v[186:187], v[186:187], v[196:197]
	v_add_f32_e32 v160, v160, v161
	v_add_f32_e32 v186, v186, v187
	v_add_f32_e32 v161, v162, v163
	v_add_f32_e32 v187, v188, v189
	v_add_f32_e32 v160, v160, v161
	v_add_f32_e32 v186, v186, v187
	v_fmamk_f32 v160, v160, 0x3a800000, v244
	v_fmamk_f32 v186, v186, 0x3a800000, v244
	v_rsq_f32_e32 v160, v160
	v_rsq_f32_e32 v186, v186
	ds_bpermute_b32 v228, v237, v160
	ds_bpermute_b32 v230, v237, v160 offset:64
	ds_bpermute_b32 v232, v237, v160 offset:128
	ds_bpermute_b32 v234, v237, v160 offset:192
	ds_bpermute_b32 v236, v237, v186
	ds_bpermute_b32 v238, v237, v186 offset:64
	ds_bpermute_b32 v240, v237, v186 offset:128
	ds_bpermute_b32 v248, v237, v186 offset:192
	s_mov_b32 s101, s71
.Lp7_rsok:
	s_waitcnt lgkmcnt(0)
	v_pk_mul_f32 v[100:101], v[100:101], v[234:235] op_sel_hi:[1,0]
	v_pk_mul_f32 v[102:103], v[102:103], v[234:235] op_sel_hi:[1,0]
	v_pk_mul_f32 v[36:37], v[36:37], v[234:235] op_sel_hi:[1,0]
	v_pk_mul_f32 v[38:39], v[38:39], v[234:235] op_sel_hi:[1,0]
	v_pk_mul_f32 v[96:97], v[96:97], v[234:235] op_sel_hi:[1,0]
	v_pk_mul_f32 v[98:99], v[98:99], v[234:235] op_sel_hi:[1,0]
	v_pk_mul_f32 v[32:33], v[32:33], v[234:235] op_sel_hi:[1,0]
	v_pk_mul_f32 v[34:35], v[34:35], v[234:235] op_sel_hi:[1,0]
	v_pk_mul_f32 v[68:69], v[68:69], v[248:249] op_sel_hi:[1,0]
	v_pk_mul_f32 v[70:71], v[70:71], v[248:249] op_sel_hi:[1,0]
	v_pk_mul_f32 v[4:5], v[4:5], v[248:249] op_sel_hi:[1,0]
	v_pk_mul_f32 v[6:7], v[6:7], v[248:249] op_sel_hi:[1,0]
	v_pk_mul_f32 v[64:65], v[64:65], v[248:249] op_sel_hi:[1,0]
	v_pk_mul_f32 v[66:67], v[66:67], v[248:249] op_sel_hi:[1,0]
	v_pk_mul_f32 v[0:1], v[0:1], v[248:249] op_sel_hi:[1,0]
	v_pk_mul_f32 v[2:3], v[2:3], v[248:249] op_sel_hi:[1,0]
	s_mov_b64 s[0:1], exec
	s_andn2_b64 exec, exec, s[40:41]
	ds_write_b128 v211, v[100:103]
	ds_write_b128 v211, v[36:39] offset:16
	ds_write_b128 v211, v[96:99] offset:512
	ds_write_b128 v211, v[32:35] offset:528
	ds_write_b128 v211, v[68:71] offset:4096
	ds_write_b128 v211, v[4:7] offset:4112
	ds_write_b128 v211, v[64:67] offset:4608
	ds_write_b128 v211, v[0:3] offset:4624
	s_mov_b64 exec, s[0:1]
	s_waitcnt lgkmcnt(0)
	s_and_b64 vcc, exec, s[94:95]
	s_cbranch_vccz .Lp7_nocomp
	s_barrier
.Lp7_nocomp:
	s_barrier
	s_and_b64 vcc, exec, s[94:95]
	s_cbranch_vccnz .Lp7_hz0
	ds_read_b128 v[160:163], v213
	ds_read_b128 v[164:167], v213 offset:512
	s_branch .Lp7_hr0
